# two redundant trailing s_barrier removed after the conversion blocks (on top of v31)
# baseline (speedup 1.0000x reference)
; __device__ __forceinline__ void lds_barrier() { asm volatile("s_waitcnt lgkmcnt(0)" ::: "memory"); __builtin_amdgcn_s_barrier(); asm volatile("" ::: "memory"); }
; __device__ __forceinline__ void convT_job(const float* __restrict__ src, bf16_t* __restrict__ dst, int K, int N, int mode, float* t) {
;     ...
;         lds_barrier();
;     }
.Ldf_dwout_skip:
.Ldf_end:
.LBB0_544:
	s_mov_b64 s[0:1], 0

; __device__ __forceinline__ unsigned cvt_pk_bf16(float lo, float hi) { unsigned r; asm volatile("v_cvt_pk_bf16_f32 %0, %1, %2" : "=v"(r) : "v"(lo), "v"(hi)); return r; }
; __device__ __forceinline__ int opaque_tid() { int t = threadIdx.x; asm volatile("" : "+v"(t)); return t; }
; __device__ __forceinline__ void lds_barrier() { asm volatile("s_waitcnt lgkmcnt(0)" ::: "memory"); __builtin_amdgcn_s_barrier(); asm volatile("" ::: "memory"); }
; __device__ __forceinline__ void convT_job(const float* __restrict__ src, bf16_t* __restrict__ dst, int K, int N, int mode, float* t) {
;     ...
;         const int n = tid >> 3, k16 = (tid & 7) * 16;
;         float v[16];
; #pragma unroll
;         for (int j = 0; j < 16; ++j) v[j] = t[(k16 + j) * 65 + n];
;         const int nn = n0 + n;
;         const int row = mode == 0 ? nn : (256 * (nn >> 7) + (nn & 127) + (mode == 2 ? 128 : 0));
;         u32x4 w0, w1; w0.x = cvt_pk_bf16(v[0], v[1]); w0.y = cvt_pk_bf16(v[2], v[3]); w0.z = cvt_pk_bf16(v[4], v[5]); w0.w = cvt_pk_bf16(v[6], v[7]);
;         w1.x = cvt_pk_bf16(v[8], v[9]); w1.y = cvt_pk_bf16(v[10], v[11]); w1.z = cvt_pk_bf16(v[12], v[13]); w1.w = cvt_pk_bf16(v[14], v[15]);
;         bf16_t* d = dst + (size_t)row * K + k0 + k16;
;         *(u32x4*)d = w0; *(u32x4*)(d + 8) = w1;
;         lds_barrier();
; __device__ __forceinline__ void phase_convert(const Params& p, unsigned char* smem) {
;     ...
;     const float4* xs = (const float4*)p.in[0]; u32x2* xd = (u32x2*)(p.ws + OFF_XB);
;     const size_t n4 = (size_t)NTOK * DM / 4, gstr = (size_t)gridDim.x * 512;
;     size_t i = (size_t)blockIdx.x * 512 + opaque_tid();
;     for (; i + 7 * gstr < n4; i += 8 * gstr) {
.Lcv_rgx_lj:
	v_add_u32_e32 v7, s41, v4
	ds_read2st64_b32 v[8:9], v7 offset0:0 offset1:1
	ds_read2st64_b32 v[10:11], v7 offset0:2 offset1:3
	ds_read2st64_b32 v[12:13], v7 offset0:4 offset1:5
	ds_read2st64_b32 v[14:15], v7 offset0:6 offset1:7
	ds_read2st64_b32 v[16:17], v7 offset0:8 offset1:9
	ds_read2st64_b32 v[18:19], v7 offset0:10 offset1:11
	ds_read2st64_b32 v[20:21], v7 offset0:12 offset1:13
	ds_read2st64_b32 v[22:23], v7 offset0:14 offset1:15
	s_mul_hi_u32 s0, s40, 0x80000001
	s_mul_i32 s1, s0, 2
	s_sub_u32 s1, s40, s1
	s_mul_hi_u32 s2, s1, 0x80000001
	s_mul_i32 s8, s2, 2
	s_sub_u32 s8, s1, s8
	s_lshl_b32 s9, s8, 6
	s_mul_i32 s9, s9, 0x100
	s_mul_i32 s28, s0, 0x8000
	s_add_u32 s9, s9, s28
	s_lshl_b32 s2, s2, 8
	s_add_u32 s9, s9, s2
	s_add_u32 s9, s9, 0x14448000
	s_add_u32 s44, s54, s9
	s_addc_u32 s45, s55, 0
	s_waitcnt lgkmcnt(6)
	v_cvt_pk_bf16_f32 v8, v8, v9
	v_cvt_pk_bf16_f32 v9, v10, v11
	s_waitcnt lgkmcnt(4)
	v_cvt_pk_bf16_f32 v10, v12, v13
	v_cvt_pk_bf16_f32 v11, v14, v15
	s_waitcnt lgkmcnt(2)
	v_cvt_pk_bf16_f32 v12, v16, v17
	v_cvt_pk_bf16_f32 v13, v18, v19
	s_waitcnt lgkmcnt(0)
	v_cvt_pk_bf16_f32 v14, v20, v21
	v_cvt_pk_bf16_f32 v15, v22, v23
	global_store_dwordx4 v5, v[8:11], s[44:45]
	global_store_dwordx4 v5, v[12:15], s[44:45] offset:16
	s_add_u32 s40, s40, s98
	s_add_u32 s41, s41, 0x8000
	s_and_b32 s41, s41, 0x1ffff
	s_cmp_lt_u32 s40, 16
	s_cbranch_scc1 .Lcv_rgx_loop
.Lcv_rgx_skip:
	s_branch .LBB0_679
.LBB0_679:
	s_load_dword s0, s[96:97], 0x10
	s_load_dword s2, s[96:97], 0x0
	s_waitcnt vmcnt(0)
	v_mov_b32_e32 v4, v234
	v_mov_b32_e32 v2, 0xe00
	s_waitcnt lgkmcnt(0)
	s_lshr_b32 s0, s0, 16
	s_cmp_lg_u32 s0, 0
	s_cselect_b64 s[0:1], -1, 0
	s_cmp_lg_u64 s[0:1], 0
	v_readlane_b32 s0, v254, 40
	v_ashrrev_i32_e32 v5, 31, v4
	v_readlane_b32 s1, v254, 41
	s_addc_u32 s2, s2, 0
	s_nop 0
	v_lshl_add_u64 v[0:1], s[0:1], 0, v[4:5]
	v_mad_u64_u32 v[2:3], s[0:1], s2, v2, v[0:1]
	s_mov_b64 s[0:1], 0x800000
	s_nop 0
	v_cmp_gt_u64_e32 vcc, s[0:1], v[2:3]
	s_and_saveexec_b64 s[0:1], vcc
	s_cbranch_execz .LBB0_683
	v_readlane_b32 s8, v254, 60
	v_readlane_b32 s9, v254, 61
	s_mul_hi_u32 s41, s2, 0xe00
	s_mul_i32 s40, s2, 0xe00
	v_lshl_add_u64 v[2:3], v[4:5], 4, s[8:9]
	v_readlane_b32 s8, v254, 62
	v_readlane_b32 s9, v254, 63
	s_lshl_b64 s[42:43], s[2:3], 12
	s_lshl_b64 s[44:45], s[2:3], 13
	s_lshl_b64 s[46:47], s[2:3], 16
	v_lshl_add_u64 v[4:5], v[4:5], 3, s[8:9]
	s_lshl_b64 s[50:51], s[2:3], 15
	s_mov_b64 s[48:49], 0
	s_mov_b64 s[8:9], 0x7fffff
